# epilogue load batching: P2 EpiK/EpiQ RMS-sum prefetch, attention unit epilogue 16 MIX/G loads prefetched with counted waits; on top of v21
# speedup vs baseline: 1.0211x; 1.0211x over previous
.LBB0_829:
	v_lshl_add_u32 v156, s10, 8, v129
	v_readlane_b32 s10, v254, 14
	v_ashrrev_i32_e32 v157, 31, v156
	v_readlane_b32 s11, v254, 15
	s_cmp_gt_i32 s8, 7
	s_cselect_b64 s[52:53], -1, 0
	v_lshl_add_u64 v[158:159], v[156:157], 2, s[10:11]
	global_load_dword v190, v[158:159], off
	global_load_dword v191, v[158:159], off offset:64
	global_load_dword v192, v[158:159], off offset:128
	global_load_dword v193, v[158:159], off offset:192
	global_load_dword v194, v[158:159], off offset:512
	global_load_dword v195, v[158:159], off offset:576
	global_load_dword v196, v[158:159], off offset:640
	global_load_dword v197, v[158:159], off offset:704
	s_waitcnt vmcnt(0)
	v_mov_b32_e32 v160, v190
	s_lshl_b32 s25, s8, 8
	s_add_i32 s14, s25, s59
	s_mov_b64 s[10:11], -1
	v_lshlrev_b32_e32 v138, 1, v140
	s_cmp_lt_i32 s8, 8
	v_fmamk_f32 v160, v160, 0x3b000000, v167
	v_mul_f32_e32 v161, 0x4b800000, v160
	v_cmp_gt_f32_e32 vcc, s66, v160
	s_nop 1
	v_cndmask_b32_e32 v160, v160, v161, vcc
	v_rsq_f32_e32 v160, v160
	s_nop 0
	v_mul_f32_e32 v161, 0x45800000, v160
	v_cndmask_b32_e32 v160, v160, v161, vcc
	v_mul_f32_e32 v160, 0x3dd53b94, v160
	v_mov_b32_e32 v161, v160
	v_pk_mul_f32 v[162:163], v[124:125], v[160:161]
	v_pk_mul_f32 v[124:125], v[120:121], v[160:161]
	v_pk_mul_f32 v[120:121], v[116:117], v[160:161]
	v_pk_mul_f32 v[116:117], v[112:113], v[160:161]
	s_cbranch_scc1 .LBB0_831
	v_lshlrev_b64 v[112:113], 7, v[156:157]
	v_lshl_add_u64 v[176:177], v[146:147], 0, v[112:113]
	global_load_dwordx4 v[168:171], v[176:177], off
	v_lshl_add_u64 v[112:113], v[144:145], 0, v[112:113]
	global_load_dwordx4 v[172:175], v[112:113], off
	v_mov_b32_e32 v161, v160
	s_lshr_b32 s10, s14, 6
	v_mov_b64_e32 v[178:179], s[18:19]
	v_pk_mul_f32 v[182:183], v[122:123], v[160:161]
	v_pk_mul_f32 v[180:181], v[126:127], v[160:161]
	v_mad_i64_i32 v[178:179], s[8:9], v156, s67, v[178:179]
	s_mul_i32 s12, s10, 0xc0
	v_lshl_add_u64 v[178:179], s[12:13], 1, v[178:179]
	v_lshl_add_u64 v[178:179], v[178:179], 0, v[138:139]
	s_mov_b64 s[10:11], 0
	s_waitcnt vmcnt(1)
	v_pk_mul_f32 v[184:185], v[182:183], v[170:171]
	v_pk_mul_f32 v[186:187], v[124:125], v[168:169]
	v_pk_mul_f32 v[170:171], v[180:181], v[170:171]
	v_pk_mul_f32 v[168:169], v[162:163], v[168:169]
	s_waitcnt vmcnt(0)
	v_pk_fma_f32 v[180:181], v[180:181], v[174:175], v[184:185] neg_lo:[0,0,1] neg_hi:[0,0,1]
	v_pk_fma_f32 v[184:185], v[162:163], v[172:173], v[186:187] neg_lo:[0,0,1] neg_hi:[0,0,1]
	v_pk_fma_f32 v[170:171], v[182:183], v[174:175], v[170:171]
	v_pk_fma_f32 v[168:169], v[124:125], v[172:173], v[168:169]
	v_cvt_pk_bf16_f32 v172, v184, v185
	v_cvt_pk_bf16_f32 v173, v180, v181
	v_cvt_pk_bf16_f32 v168, v168, v169
	v_cvt_pk_bf16_f32 v169, v170, v171
	global_store_dwordx2 v[178:179], v[172:173], off offset:256
	global_store_dwordx2 v[178:179], v[168:169], off offset:320
	global_load_dwordx4 v[168:171], v[176:177], off
	s_nop 0
	global_load_dwordx4 v[172:175], v[112:113], off
	v_pk_mul_f32 v[176:177], v[114:115], v[160:161]
	v_pk_mul_f32 v[112:113], v[118:119], v[160:161]
	s_waitcnt vmcnt(1)
	v_pk_mul_f32 v[180:181], v[176:177], v[170:171]
	v_pk_mul_f32 v[182:183], v[116:117], v[168:169]
	v_pk_mul_f32 v[170:171], v[112:113], v[170:171]
	v_pk_mul_f32 v[168:169], v[120:121], v[168:169]
	s_waitcnt vmcnt(0)
	v_pk_fma_f32 v[112:113], v[112:113], v[174:175], v[180:181] neg_lo:[0,0,1] neg_hi:[0,0,1]
	v_pk_fma_f32 v[180:181], v[120:121], v[172:173], v[182:183] neg_lo:[0,0,1] neg_hi:[0,0,1]
	v_pk_fma_f32 v[170:171], v[176:177], v[174:175], v[170:171]
	v_pk_fma_f32 v[168:169], v[116:117], v[172:173], v[168:169]
	v_cvt_pk_bf16_f32 v172, v180, v181
	v_cvt_pk_bf16_f32 v173, v112, v113
	v_cvt_pk_bf16_f32 v112, v168, v169
	v_cvt_pk_bf16_f32 v113, v170, v171
	global_store_dwordx2 v[178:179], v[172:173], off offset:1024
	global_store_dwordx2 v[178:179], v[112:113], off offset:1088

.LBB0_833:
	s_nop 1
	v_mov_b32_e32 v113, v191
	s_nop 0
	v_cndmask_b32_e64 v116, 0, 1, s[52:53]
	v_cmp_ne_u32_e64 s[8:9], 1, v116
	v_or_b32_e32 v114, 16, v156
	s_mov_b64 s[54:55], -1
	s_andn2_b64 vcc, exec, s[52:53]
	v_fmamk_f32 v113, v113, 0x3b000000, v167
	v_mul_f32_e32 v115, 0x4b800000, v113
	v_cmp_gt_f32_e64 s[10:11], s66, v113
	s_nop 1
	v_cndmask_b32_e64 v113, v113, v115, s[10:11]
	v_rsq_f32_e32 v113, v113
	v_ashrrev_i32_e32 v115, 31, v114
	v_mul_f32_e32 v116, 0x45800000, v113
	v_cndmask_b32_e64 v113, v113, v116, s[10:11]
	v_mul_f32_e32 v116, 0x3dd53b94, v113
	v_mov_b32_e32 v117, v116
	v_pk_mul_f32 v[108:109], v[108:109], v[116:117]
	v_pk_mul_f32 v[104:105], v[104:105], v[116:117]
	v_pk_mul_f32 v[100:101], v[100:101], v[116:117]
	v_pk_mul_f32 v[96:97], v[96:97], v[116:117]
	s_cbranch_vccnz .LBB0_835
	v_lshlrev_b64 v[122:123], 7, v[114:115]
	v_lshl_add_u64 v[126:127], v[146:147], 0, v[122:123]
	global_load_dwordx4 v[118:121], v[126:127], off
	v_lshl_add_u64 v[160:161], v[144:145], 0, v[122:123]
	global_load_dwordx4 v[122:125], v[160:161], off
	v_mov_b32_e32 v117, v116
	s_lshr_b32 s12, s14, 6
	v_mov_b64_e32 v[162:163], s[18:19]
	v_pk_mul_f32 v[170:171], v[106:107], v[116:117]
	v_pk_mul_f32 v[168:169], v[110:111], v[116:117]
	v_mad_i64_i32 v[162:163], s[10:11], v114, s67, v[162:163]
	s_mulk_i32 s12, 0xc0
	v_lshl_add_u64 v[162:163], s[12:13], 1, v[162:163]
	v_lshl_add_u64 v[162:163], v[162:163], 0, v[138:139]
	s_mov_b64 s[54:55], 0
	s_waitcnt vmcnt(1)
	v_pk_mul_f32 v[172:173], v[170:171], v[120:121]
	v_pk_mul_f32 v[174:175], v[104:105], v[118:119]
	v_pk_mul_f32 v[120:121], v[168:169], v[120:121]
	v_pk_mul_f32 v[118:119], v[108:109], v[118:119]
	s_waitcnt vmcnt(0)
	v_pk_fma_f32 v[168:169], v[168:169], v[124:125], v[172:173] neg_lo:[0,0,1] neg_hi:[0,0,1]
	v_pk_fma_f32 v[172:173], v[108:109], v[122:123], v[174:175] neg_lo:[0,0,1] neg_hi:[0,0,1]
	v_pk_fma_f32 v[120:121], v[170:171], v[124:125], v[120:121]
	v_pk_fma_f32 v[118:119], v[104:105], v[122:123], v[118:119]
	v_cvt_pk_bf16_f32 v122, v172, v173
	v_cvt_pk_bf16_f32 v123, v168, v169
	v_cvt_pk_bf16_f32 v118, v118, v119
	v_cvt_pk_bf16_f32 v119, v120, v121
	global_store_dwordx2 v[162:163], v[122:123], off offset:256
	global_store_dwordx2 v[162:163], v[118:119], off offset:320
	global_load_dwordx4 v[118:121], v[126:127], off
	s_nop 0
	global_load_dwordx4 v[122:125], v[160:161], off
	v_pk_mul_f32 v[160:161], v[98:99], v[116:117]
	v_pk_mul_f32 v[126:127], v[102:103], v[116:117]
	s_waitcnt vmcnt(1)
	v_pk_mul_f32 v[168:169], v[160:161], v[120:121]
	v_pk_mul_f32 v[170:171], v[96:97], v[118:119]
	v_pk_mul_f32 v[120:121], v[126:127], v[120:121]
	v_pk_mul_f32 v[118:119], v[100:101], v[118:119]
	s_waitcnt vmcnt(0)
	v_pk_fma_f32 v[126:127], v[126:127], v[124:125], v[168:169] neg_lo:[0,0,1] neg_hi:[0,0,1]
	v_pk_fma_f32 v[168:169], v[100:101], v[122:123], v[170:171] neg_lo:[0,0,1] neg_hi:[0,0,1]
	v_pk_fma_f32 v[120:121], v[160:161], v[124:125], v[120:121]
	v_pk_fma_f32 v[118:119], v[96:97], v[122:123], v[118:119]
	v_cvt_pk_bf16_f32 v122, v168, v169
	v_cvt_pk_bf16_f32 v123, v126, v127
	v_cvt_pk_bf16_f32 v118, v118, v119
	v_cvt_pk_bf16_f32 v119, v120, v121
	global_store_dwordx2 v[162:163], v[122:123], off offset:1024
	global_store_dwordx2 v[162:163], v[118:119], off offset:1088

.LBB0_837:
	s_nop 1
	v_mov_b32_e32 v97, v192
	v_or_b32_e32 v96, 32, v156
	s_mov_b64 s[52:53], -1
	s_and_b64 vcc, exec, s[8:9]
	v_fmamk_f32 v97, v97, 0x3b000000, v167
	v_mul_f32_e32 v98, 0x4b800000, v97
	v_cmp_gt_f32_e64 s[10:11], s66, v97
	s_nop 1
	v_cndmask_b32_e64 v97, v97, v98, s[10:11]
	v_rsq_f32_e32 v98, v97
	v_ashrrev_i32_e32 v97, 31, v96
	v_mul_f32_e32 v99, 0x45800000, v98
	v_cndmask_b32_e64 v98, v98, v99, s[10:11]
	v_mul_f32_e32 v98, 0x3dd53b94, v98
	v_mov_b32_e32 v99, v98
	v_pk_mul_f32 v[92:93], v[92:93], v[98:99]
	v_pk_mul_f32 v[88:89], v[88:89], v[98:99]
	v_pk_mul_f32 v[84:85], v[84:85], v[98:99]
	v_pk_mul_f32 v[80:81], v[80:81], v[98:99]
	s_cbranch_vccnz .LBB0_839
	v_lshlrev_b64 v[104:105], 7, v[96:97]
	v_lshl_add_u64 v[108:109], v[146:147], 0, v[104:105]
	global_load_dwordx4 v[100:103], v[108:109], off
	v_lshl_add_u64 v[110:111], v[144:145], 0, v[104:105]
	global_load_dwordx4 v[104:107], v[110:111], off
	v_mov_b32_e32 v99, v98
	s_lshr_b32 s12, s14, 6
	v_mov_b64_e32 v[114:115], s[18:19]
	v_pk_mul_f32 v[118:119], v[90:91], v[98:99]
	v_pk_mul_f32 v[116:117], v[94:95], v[98:99]
	v_mad_i64_i32 v[114:115], s[10:11], v96, s67, v[114:115]
	s_mulk_i32 s12, 0xc0
	v_lshl_add_u64 v[114:115], s[12:13], 1, v[114:115]
	v_lshl_add_u64 v[114:115], v[114:115], 0, v[138:139]
	s_mov_b64 s[52:53], 0
	s_waitcnt vmcnt(1)
	v_pk_mul_f32 v[120:121], v[118:119], v[102:103]
	v_pk_mul_f32 v[122:123], v[88:89], v[100:101]
	v_pk_mul_f32 v[102:103], v[116:117], v[102:103]
	v_pk_mul_f32 v[100:101], v[92:93], v[100:101]
	s_waitcnt vmcnt(0)
	v_pk_fma_f32 v[116:117], v[116:117], v[106:107], v[120:121] neg_lo:[0,0,1] neg_hi:[0,0,1]
	v_pk_fma_f32 v[120:121], v[92:93], v[104:105], v[122:123] neg_lo:[0,0,1] neg_hi:[0,0,1]
	v_pk_fma_f32 v[102:103], v[118:119], v[106:107], v[102:103]
	v_pk_fma_f32 v[100:101], v[88:89], v[104:105], v[100:101]
	v_cvt_pk_bf16_f32 v104, v120, v121
	v_cvt_pk_bf16_f32 v105, v116, v117
	v_cvt_pk_bf16_f32 v100, v100, v101
	v_cvt_pk_bf16_f32 v101, v102, v103
	global_store_dwordx2 v[114:115], v[104:105], off offset:256
	global_store_dwordx2 v[114:115], v[100:101], off offset:320
	global_load_dwordx4 v[100:103], v[108:109], off
	s_nop 0
	global_load_dwordx4 v[104:107], v[110:111], off
	v_pk_mul_f32 v[110:111], v[82:83], v[98:99]
	v_pk_mul_f32 v[108:109], v[86:87], v[98:99]
	s_waitcnt vmcnt(1)
	v_pk_mul_f32 v[116:117], v[110:111], v[102:103]
	v_pk_mul_f32 v[118:119], v[80:81], v[100:101]
	v_pk_mul_f32 v[102:103], v[108:109], v[102:103]
	v_pk_mul_f32 v[100:101], v[84:85], v[100:101]
	s_waitcnt vmcnt(0)
	v_pk_fma_f32 v[108:109], v[108:109], v[106:107], v[116:117] neg_lo:[0,0,1] neg_hi:[0,0,1]
	v_pk_fma_f32 v[116:117], v[84:85], v[104:105], v[118:119] neg_lo:[0,0,1] neg_hi:[0,0,1]
	v_pk_fma_f32 v[102:103], v[110:111], v[106:107], v[102:103]
	v_pk_fma_f32 v[100:101], v[80:81], v[104:105], v[100:101]
	v_cvt_pk_bf16_f32 v104, v116, v117
	v_cvt_pk_bf16_f32 v105, v108, v109
	v_cvt_pk_bf16_f32 v100, v100, v101
	v_cvt_pk_bf16_f32 v101, v102, v103
	global_store_dwordx2 v[114:115], v[104:105], off offset:1024
	global_store_dwordx2 v[114:115], v[100:101], off offset:1088

.LBB0_841:
	s_nop 1
	v_mov_b32_e32 v81, v193
	v_or_b32_e32 v80, 48, v156
	s_mov_b64 s[52:53], -1
	s_and_b64 vcc, exec, s[8:9]
	v_fmamk_f32 v81, v81, 0x3b000000, v167
	v_mul_f32_e32 v82, 0x4b800000, v81
	v_cmp_gt_f32_e64 s[10:11], s66, v81
	s_nop 1
	v_cndmask_b32_e64 v81, v81, v82, s[10:11]
	v_rsq_f32_e32 v82, v81
	v_ashrrev_i32_e32 v81, 31, v80
	v_mul_f32_e32 v83, 0x45800000, v82
	v_cndmask_b32_e64 v82, v82, v83, s[10:11]
	v_mul_f32_e32 v82, 0x3dd53b94, v82
	v_mov_b32_e32 v83, v82
	v_pk_mul_f32 v[76:77], v[76:77], v[82:83]
	v_pk_mul_f32 v[72:73], v[72:73], v[82:83]
	v_pk_mul_f32 v[68:69], v[68:69], v[82:83]
	v_pk_mul_f32 v[64:65], v[64:65], v[82:83]
	s_cbranch_vccnz .LBB0_843
	v_lshlrev_b64 v[88:89], 7, v[80:81]
	v_lshl_add_u64 v[92:93], v[146:147], 0, v[88:89]
	global_load_dwordx4 v[84:87], v[92:93], off
	v_lshl_add_u64 v[94:95], v[144:145], 0, v[88:89]
	global_load_dwordx4 v[88:91], v[94:95], off
	v_mov_b32_e32 v83, v82
	s_lshr_b32 s12, s14, 6
	v_mov_b64_e32 v[96:97], s[18:19]
	v_pk_mul_f32 v[100:101], v[74:75], v[82:83]
	v_pk_mul_f32 v[98:99], v[78:79], v[82:83]
	v_mad_i64_i32 v[96:97], s[10:11], v80, s67, v[96:97]
	s_mulk_i32 s12, 0xc0
	v_lshl_add_u64 v[96:97], s[12:13], 1, v[96:97]
	v_lshl_add_u64 v[96:97], v[96:97], 0, v[138:139]
	s_mov_b64 s[52:53], 0
	s_waitcnt vmcnt(1)
	v_pk_mul_f32 v[102:103], v[100:101], v[86:87]
	v_pk_mul_f32 v[104:105], v[72:73], v[84:85]
	v_pk_mul_f32 v[86:87], v[98:99], v[86:87]
	v_pk_mul_f32 v[84:85], v[76:77], v[84:85]
	s_waitcnt vmcnt(0)
	v_pk_fma_f32 v[98:99], v[98:99], v[90:91], v[102:103] neg_lo:[0,0,1] neg_hi:[0,0,1]
	v_pk_fma_f32 v[102:103], v[76:77], v[88:89], v[104:105] neg_lo:[0,0,1] neg_hi:[0,0,1]
	v_pk_fma_f32 v[86:87], v[100:101], v[90:91], v[86:87]
	v_pk_fma_f32 v[84:85], v[72:73], v[88:89], v[84:85]
	v_cvt_pk_bf16_f32 v88, v102, v103
	v_cvt_pk_bf16_f32 v89, v98, v99
	v_cvt_pk_bf16_f32 v84, v84, v85
	v_cvt_pk_bf16_f32 v85, v86, v87
	global_store_dwordx2 v[96:97], v[88:89], off offset:256
	global_store_dwordx2 v[96:97], v[84:85], off offset:320
	global_load_dwordx4 v[84:87], v[92:93], off
	s_nop 0
	global_load_dwordx4 v[88:91], v[94:95], off
	v_pk_mul_f32 v[94:95], v[66:67], v[82:83]
	v_pk_mul_f32 v[92:93], v[70:71], v[82:83]
	s_waitcnt vmcnt(1)
	v_pk_mul_f32 v[98:99], v[94:95], v[86:87]
	v_pk_mul_f32 v[100:101], v[64:65], v[84:85]
	v_pk_mul_f32 v[86:87], v[92:93], v[86:87]
	v_pk_mul_f32 v[84:85], v[68:69], v[84:85]
	s_waitcnt vmcnt(0)
	v_pk_fma_f32 v[92:93], v[92:93], v[90:91], v[98:99] neg_lo:[0,0,1] neg_hi:[0,0,1]
	v_pk_fma_f32 v[98:99], v[68:69], v[88:89], v[100:101] neg_lo:[0,0,1] neg_hi:[0,0,1]
	v_pk_fma_f32 v[86:87], v[94:95], v[90:91], v[86:87]
	v_pk_fma_f32 v[84:85], v[64:65], v[88:89], v[84:85]
	v_cvt_pk_bf16_f32 v88, v98, v99
	v_cvt_pk_bf16_f32 v89, v92, v93
	v_cvt_pk_bf16_f32 v84, v84, v85
	v_cvt_pk_bf16_f32 v85, v86, v87
	global_store_dwordx2 v[96:97], v[88:89], off offset:1024
	global_store_dwordx2 v[96:97], v[84:85], off offset:1088

.LBB0_845:
	s_nop 1
	v_mov_b32_e32 v65, v194
	v_add_u32_e32 v64, 0x80, v156
	s_mov_b64 s[52:53], -1
	s_and_b64 vcc, exec, s[8:9]
	v_fmamk_f32 v65, v65, 0x3b000000, v167
	v_mul_f32_e32 v66, 0x4b800000, v65
	v_cmp_gt_f32_e64 s[10:11], s66, v65
	s_nop 1
	v_cndmask_b32_e64 v65, v65, v66, s[10:11]
	v_rsq_f32_e32 v66, v65
	v_ashrrev_i32_e32 v65, 31, v64
	v_mul_f32_e32 v67, 0x45800000, v66
	v_cndmask_b32_e64 v66, v66, v67, s[10:11]
	v_mul_f32_e32 v66, 0x3dd53b94, v66
	v_mov_b32_e32 v67, v66
	v_pk_mul_f32 v[60:61], v[60:61], v[66:67]
	v_pk_mul_f32 v[56:57], v[56:57], v[66:67]
	v_pk_mul_f32 v[52:53], v[52:53], v[66:67]
	v_pk_mul_f32 v[48:49], v[48:49], v[66:67]
	s_cbranch_vccnz .LBB0_847
	v_lshlrev_b64 v[72:73], 7, v[64:65]
	v_lshl_add_u64 v[76:77], v[146:147], 0, v[72:73]
	global_load_dwordx4 v[68:71], v[76:77], off
	v_lshl_add_u64 v[78:79], v[144:145], 0, v[72:73]
	global_load_dwordx4 v[72:75], v[78:79], off
	v_mov_b32_e32 v67, v66
	s_lshr_b32 s12, s14, 6
	v_mov_b64_e32 v[80:81], s[18:19]
	v_pk_mul_f32 v[84:85], v[58:59], v[66:67]
	v_pk_mul_f32 v[82:83], v[62:63], v[66:67]
	v_mad_i64_i32 v[80:81], s[10:11], v64, s67, v[80:81]
	s_mulk_i32 s12, 0xc0
	v_lshl_add_u64 v[80:81], s[12:13], 1, v[80:81]
	v_lshl_add_u64 v[80:81], v[80:81], 0, v[138:139]
	s_mov_b64 s[52:53], 0
	s_waitcnt vmcnt(1)
	v_pk_mul_f32 v[86:87], v[84:85], v[70:71]
	v_pk_mul_f32 v[88:89], v[56:57], v[68:69]
	v_pk_mul_f32 v[70:71], v[82:83], v[70:71]
	v_pk_mul_f32 v[68:69], v[60:61], v[68:69]
	s_waitcnt vmcnt(0)
	v_pk_fma_f32 v[82:83], v[82:83], v[74:75], v[86:87] neg_lo:[0,0,1] neg_hi:[0,0,1]
	v_pk_fma_f32 v[86:87], v[60:61], v[72:73], v[88:89] neg_lo:[0,0,1] neg_hi:[0,0,1]
	v_pk_fma_f32 v[70:71], v[84:85], v[74:75], v[70:71]
	v_pk_fma_f32 v[68:69], v[56:57], v[72:73], v[68:69]
	v_cvt_pk_bf16_f32 v72, v86, v87
	v_cvt_pk_bf16_f32 v73, v82, v83
	v_cvt_pk_bf16_f32 v68, v68, v69
	v_cvt_pk_bf16_f32 v69, v70, v71
	global_store_dwordx2 v[80:81], v[72:73], off offset:256
	global_store_dwordx2 v[80:81], v[68:69], off offset:320
	global_load_dwordx4 v[68:71], v[76:77], off
	s_nop 0
	global_load_dwordx4 v[72:75], v[78:79], off
	v_pk_mul_f32 v[78:79], v[50:51], v[66:67]
	v_pk_mul_f32 v[76:77], v[54:55], v[66:67]
	s_waitcnt vmcnt(1)
	v_pk_mul_f32 v[82:83], v[78:79], v[70:71]
	v_pk_mul_f32 v[84:85], v[48:49], v[68:69]
	v_pk_mul_f32 v[70:71], v[76:77], v[70:71]
	v_pk_mul_f32 v[68:69], v[52:53], v[68:69]
	s_waitcnt vmcnt(0)
	v_pk_fma_f32 v[76:77], v[76:77], v[74:75], v[82:83] neg_lo:[0,0,1] neg_hi:[0,0,1]
	v_pk_fma_f32 v[82:83], v[52:53], v[72:73], v[84:85] neg_lo:[0,0,1] neg_hi:[0,0,1]
	v_pk_fma_f32 v[70:71], v[78:79], v[74:75], v[70:71]
	v_pk_fma_f32 v[68:69], v[48:49], v[72:73], v[68:69]
	v_cvt_pk_bf16_f32 v72, v82, v83
	v_cvt_pk_bf16_f32 v73, v76, v77
	v_cvt_pk_bf16_f32 v68, v68, v69
	v_cvt_pk_bf16_f32 v69, v70, v71
	global_store_dwordx2 v[80:81], v[72:73], off offset:1024
	global_store_dwordx2 v[80:81], v[68:69], off offset:1088

.LBB0_849:
	s_nop 1
	v_mov_b32_e32 v49, v195
	v_add_u32_e32 v48, 0x90, v156
	s_mov_b64 s[52:53], -1
	s_and_b64 vcc, exec, s[8:9]
	v_fmamk_f32 v49, v49, 0x3b000000, v167
	v_mul_f32_e32 v50, 0x4b800000, v49
	v_cmp_gt_f32_e64 s[10:11], s66, v49
	s_nop 1
	v_cndmask_b32_e64 v49, v49, v50, s[10:11]
	v_rsq_f32_e32 v50, v49
	v_ashrrev_i32_e32 v49, 31, v48
	v_mul_f32_e32 v51, 0x45800000, v50
	v_cndmask_b32_e64 v50, v50, v51, s[10:11]
	v_mul_f32_e32 v50, 0x3dd53b94, v50
	v_mov_b32_e32 v51, v50
	v_pk_mul_f32 v[44:45], v[44:45], v[50:51]
	v_pk_mul_f32 v[40:41], v[40:41], v[50:51]
	v_pk_mul_f32 v[36:37], v[36:37], v[50:51]
	v_pk_mul_f32 v[32:33], v[32:33], v[50:51]
	s_cbranch_vccnz .LBB0_851
	v_lshlrev_b64 v[56:57], 7, v[48:49]
	v_lshl_add_u64 v[60:61], v[146:147], 0, v[56:57]
	global_load_dwordx4 v[52:55], v[60:61], off
	v_lshl_add_u64 v[62:63], v[144:145], 0, v[56:57]
	global_load_dwordx4 v[56:59], v[62:63], off
	v_mov_b32_e32 v51, v50
	s_lshr_b32 s12, s14, 6
	v_mov_b64_e32 v[64:65], s[18:19]
	v_pk_mul_f32 v[68:69], v[42:43], v[50:51]
	v_pk_mul_f32 v[66:67], v[46:47], v[50:51]
	v_mad_i64_i32 v[64:65], s[10:11], v48, s67, v[64:65]
	s_mulk_i32 s12, 0xc0
	v_lshl_add_u64 v[64:65], s[12:13], 1, v[64:65]
	v_lshl_add_u64 v[64:65], v[64:65], 0, v[138:139]
	s_mov_b64 s[52:53], 0
	s_waitcnt vmcnt(1)
	v_pk_mul_f32 v[70:71], v[68:69], v[54:55]
	v_pk_mul_f32 v[72:73], v[40:41], v[52:53]
	v_pk_mul_f32 v[54:55], v[66:67], v[54:55]
	v_pk_mul_f32 v[52:53], v[44:45], v[52:53]
	s_waitcnt vmcnt(0)
	v_pk_fma_f32 v[66:67], v[66:67], v[58:59], v[70:71] neg_lo:[0,0,1] neg_hi:[0,0,1]
	v_pk_fma_f32 v[70:71], v[44:45], v[56:57], v[72:73] neg_lo:[0,0,1] neg_hi:[0,0,1]
	v_pk_fma_f32 v[54:55], v[68:69], v[58:59], v[54:55]
	v_pk_fma_f32 v[52:53], v[40:41], v[56:57], v[52:53]
	v_cvt_pk_bf16_f32 v56, v70, v71
	v_cvt_pk_bf16_f32 v57, v66, v67
	v_cvt_pk_bf16_f32 v52, v52, v53
	v_cvt_pk_bf16_f32 v53, v54, v55
	global_store_dwordx2 v[64:65], v[56:57], off offset:256
	global_store_dwordx2 v[64:65], v[52:53], off offset:320
	global_load_dwordx4 v[52:55], v[60:61], off
	s_nop 0
	global_load_dwordx4 v[56:59], v[62:63], off
	v_pk_mul_f32 v[62:63], v[34:35], v[50:51]
	v_pk_mul_f32 v[60:61], v[38:39], v[50:51]
	s_waitcnt vmcnt(1)
	v_pk_mul_f32 v[66:67], v[62:63], v[54:55]
	v_pk_mul_f32 v[68:69], v[32:33], v[52:53]
	v_pk_mul_f32 v[54:55], v[60:61], v[54:55]
	v_pk_mul_f32 v[52:53], v[36:37], v[52:53]
	s_waitcnt vmcnt(0)
	v_pk_fma_f32 v[60:61], v[60:61], v[58:59], v[66:67] neg_lo:[0,0,1] neg_hi:[0,0,1]
	v_pk_fma_f32 v[66:67], v[36:37], v[56:57], v[68:69] neg_lo:[0,0,1] neg_hi:[0,0,1]
	v_pk_fma_f32 v[54:55], v[62:63], v[58:59], v[54:55]
	v_pk_fma_f32 v[52:53], v[32:33], v[56:57], v[52:53]
	v_cvt_pk_bf16_f32 v56, v66, v67
	v_cvt_pk_bf16_f32 v57, v60, v61
	v_cvt_pk_bf16_f32 v52, v52, v53
	v_cvt_pk_bf16_f32 v53, v54, v55
	global_store_dwordx2 v[64:65], v[56:57], off offset:1024
	global_store_dwordx2 v[64:65], v[52:53], off offset:1088

.LBB0_853:
	s_nop 1
	v_mov_b32_e32 v33, v196
	v_add_u32_e32 v32, 0xa0, v156
	s_mov_b64 s[52:53], -1
	s_and_b64 vcc, exec, s[8:9]
	v_fmamk_f32 v33, v33, 0x3b000000, v167
	v_mul_f32_e32 v34, 0x4b800000, v33
	v_cmp_gt_f32_e64 s[10:11], s66, v33
	s_nop 1
	v_cndmask_b32_e64 v33, v33, v34, s[10:11]
	v_rsq_f32_e32 v34, v33
	v_ashrrev_i32_e32 v33, 31, v32
	v_mul_f32_e32 v35, 0x45800000, v34
	v_cndmask_b32_e64 v34, v34, v35, s[10:11]
	v_mul_f32_e32 v34, 0x3dd53b94, v34
	v_mov_b32_e32 v35, v34
	v_pk_mul_f32 v[28:29], v[28:29], v[34:35]
	v_pk_mul_f32 v[24:25], v[24:25], v[34:35]
	v_pk_mul_f32 v[20:21], v[20:21], v[34:35]
	v_pk_mul_f32 v[16:17], v[16:17], v[34:35]
	s_cbranch_vccnz .LBB0_855
	v_lshlrev_b64 v[40:41], 7, v[32:33]
	v_lshl_add_u64 v[44:45], v[146:147], 0, v[40:41]
	global_load_dwordx4 v[36:39], v[44:45], off
	v_lshl_add_u64 v[46:47], v[144:145], 0, v[40:41]
	global_load_dwordx4 v[40:43], v[46:47], off
	v_mov_b32_e32 v35, v34
	s_lshr_b32 s12, s14, 6
	v_mov_b64_e32 v[48:49], s[18:19]
	v_pk_mul_f32 v[52:53], v[26:27], v[34:35]
	v_pk_mul_f32 v[50:51], v[30:31], v[34:35]
	v_mad_i64_i32 v[48:49], s[10:11], v32, s67, v[48:49]
	s_mulk_i32 s12, 0xc0
	v_lshl_add_u64 v[48:49], s[12:13], 1, v[48:49]
	v_lshl_add_u64 v[48:49], v[48:49], 0, v[138:139]
	s_mov_b64 s[52:53], 0
	s_waitcnt vmcnt(1)
	v_pk_mul_f32 v[54:55], v[52:53], v[38:39]
	v_pk_mul_f32 v[56:57], v[24:25], v[36:37]
	v_pk_mul_f32 v[38:39], v[50:51], v[38:39]
	v_pk_mul_f32 v[36:37], v[28:29], v[36:37]
	s_waitcnt vmcnt(0)
	v_pk_fma_f32 v[50:51], v[50:51], v[42:43], v[54:55] neg_lo:[0,0,1] neg_hi:[0,0,1]
	v_pk_fma_f32 v[54:55], v[28:29], v[40:41], v[56:57] neg_lo:[0,0,1] neg_hi:[0,0,1]
	v_pk_fma_f32 v[38:39], v[52:53], v[42:43], v[38:39]
	v_pk_fma_f32 v[36:37], v[24:25], v[40:41], v[36:37]
	v_cvt_pk_bf16_f32 v40, v54, v55
	v_cvt_pk_bf16_f32 v41, v50, v51
	v_cvt_pk_bf16_f32 v36, v36, v37
	v_cvt_pk_bf16_f32 v37, v38, v39
	global_store_dwordx2 v[48:49], v[40:41], off offset:256
	global_store_dwordx2 v[48:49], v[36:37], off offset:320
	global_load_dwordx4 v[36:39], v[44:45], off
	s_nop 0
	global_load_dwordx4 v[40:43], v[46:47], off
	v_pk_mul_f32 v[46:47], v[18:19], v[34:35]
	v_pk_mul_f32 v[44:45], v[22:23], v[34:35]
	s_waitcnt vmcnt(1)
	v_pk_mul_f32 v[50:51], v[46:47], v[38:39]
	v_pk_mul_f32 v[52:53], v[16:17], v[36:37]
	v_pk_mul_f32 v[38:39], v[44:45], v[38:39]
	v_pk_mul_f32 v[36:37], v[20:21], v[36:37]
	s_waitcnt vmcnt(0)
	v_pk_fma_f32 v[44:45], v[44:45], v[42:43], v[50:51] neg_lo:[0,0,1] neg_hi:[0,0,1]
	v_pk_fma_f32 v[50:51], v[20:21], v[40:41], v[52:53] neg_lo:[0,0,1] neg_hi:[0,0,1]
	v_pk_fma_f32 v[38:39], v[46:47], v[42:43], v[38:39]
	v_pk_fma_f32 v[36:37], v[16:17], v[40:41], v[36:37]
	v_cvt_pk_bf16_f32 v40, v50, v51
	v_cvt_pk_bf16_f32 v41, v44, v45
	v_cvt_pk_bf16_f32 v36, v36, v37
	v_cvt_pk_bf16_f32 v37, v38, v39
	global_store_dwordx2 v[48:49], v[40:41], off offset:1024
	global_store_dwordx2 v[48:49], v[36:37], off offset:1088

.LBB0_857:
	s_nop 1
	v_mov_b32_e32 v17, v197
	v_add_u32_e32 v16, 0xb0, v156
	s_mov_b64 s[52:53], -1
	s_and_b64 vcc, exec, s[8:9]
	v_fmamk_f32 v17, v17, 0x3b000000, v167
	v_mul_f32_e32 v18, 0x4b800000, v17
	v_cmp_gt_f32_e64 s[10:11], s66, v17
	s_nop 1
	v_cndmask_b32_e64 v17, v17, v18, s[10:11]
	v_rsq_f32_e32 v18, v17
	v_ashrrev_i32_e32 v17, 31, v16
	v_mul_f32_e32 v19, 0x45800000, v18
	v_cndmask_b32_e64 v18, v18, v19, s[10:11]
	v_mul_f32_e32 v18, 0x3dd53b94, v18
	v_mov_b32_e32 v19, v18
	v_pk_mul_f32 v[12:13], v[12:13], v[18:19]
	v_pk_mul_f32 v[8:9], v[8:9], v[18:19]
	v_pk_mul_f32 v[4:5], v[4:5], v[18:19]
	v_pk_mul_f32 v[0:1], v[0:1], v[18:19]
	s_cbranch_vccnz .LBB0_860
	v_lshlrev_b64 v[24:25], 7, v[16:17]
	v_lshl_add_u64 v[28:29], v[146:147], 0, v[24:25]
	global_load_dwordx4 v[20:23], v[28:29], off
	v_lshl_add_u64 v[30:31], v[144:145], 0, v[24:25]
	global_load_dwordx4 v[24:27], v[30:31], off
	v_mov_b32_e32 v19, v18
	s_lshr_b32 s10, s14, 6
	v_mov_b64_e32 v[32:33], s[18:19]
	v_pk_mul_f32 v[36:37], v[10:11], v[18:19]
	v_pk_mul_f32 v[34:35], v[14:15], v[18:19]
	v_mad_i64_i32 v[32:33], s[8:9], v16, s67, v[32:33]
	s_mul_i32 s12, s10, 0xc0
	v_lshl_add_u64 v[32:33], s[12:13], 1, v[32:33]
	v_lshl_add_u64 v[32:33], v[32:33], 0, v[138:139]
	s_waitcnt vmcnt(1)
	v_pk_mul_f32 v[38:39], v[36:37], v[22:23]
	v_pk_mul_f32 v[40:41], v[8:9], v[20:21]
	v_pk_mul_f32 v[22:23], v[34:35], v[22:23]
	v_pk_mul_f32 v[20:21], v[12:13], v[20:21]
	s_waitcnt vmcnt(0)
	v_pk_fma_f32 v[34:35], v[34:35], v[26:27], v[38:39] neg_lo:[0,0,1] neg_hi:[0,0,1]
	v_pk_fma_f32 v[38:39], v[12:13], v[24:25], v[40:41] neg_lo:[0,0,1] neg_hi:[0,0,1]
	v_pk_fma_f32 v[22:23], v[36:37], v[26:27], v[22:23]
	v_pk_fma_f32 v[20:21], v[8:9], v[24:25], v[20:21]
	v_cvt_pk_bf16_f32 v24, v38, v39
	v_cvt_pk_bf16_f32 v25, v34, v35
	v_cvt_pk_bf16_f32 v20, v20, v21
	v_cvt_pk_bf16_f32 v21, v22, v23
	global_store_dwordx2 v[32:33], v[24:25], off offset:256
	global_store_dwordx2 v[32:33], v[20:21], off offset:320
	global_load_dwordx4 v[20:23], v[28:29], off
	s_nop 0
	global_load_dwordx4 v[24:27], v[30:31], off
	v_pk_mul_f32 v[30:31], v[2:3], v[18:19]
	v_pk_mul_f32 v[28:29], v[6:7], v[18:19]
	s_waitcnt vmcnt(1)
	v_pk_mul_f32 v[34:35], v[30:31], v[22:23]
	v_pk_mul_f32 v[36:37], v[0:1], v[20:21]
	v_pk_mul_f32 v[22:23], v[28:29], v[22:23]
	v_pk_mul_f32 v[20:21], v[4:5], v[20:21]
	s_waitcnt vmcnt(0)
	v_pk_fma_f32 v[28:29], v[28:29], v[26:27], v[34:35] neg_lo:[0,0,1] neg_hi:[0,0,1]
	v_pk_fma_f32 v[34:35], v[4:5], v[24:25], v[36:37] neg_lo:[0,0,1] neg_hi:[0,0,1]
	v_pk_fma_f32 v[22:23], v[30:31], v[26:27], v[22:23]
	v_pk_fma_f32 v[20:21], v[0:1], v[24:25], v[20:21]
	v_cvt_pk_bf16_f32 v24, v34, v35
	v_cvt_pk_bf16_f32 v25, v28, v29
	v_cvt_pk_bf16_f32 v20, v20, v21
	v_cvt_pk_bf16_f32 v21, v22, v23
	global_store_dwordx2 v[32:33], v[24:25], off offset:1024
	global_store_dwordx2 v[32:33], v[20:21], off offset:1088
	s_cbranch_execz .LBB0_861

.LBB0_885:
	v_lshl_add_u32 v148, s44, 8, v129
	v_lshlrev_b32_e32 v198, 2, v148
	global_load_dword v190, v198, s[30:31]
	v_add_u32_e32 v199, 16, v148
	v_lshlrev_b32_e32 v199, 2, v199
	global_load_dword v191, v199, s[30:31]
	v_add_u32_e32 v198, 32, v148
	v_lshlrev_b32_e32 v198, 2, v198
	global_load_dword v192, v198, s[30:31]
	v_add_u32_e32 v199, 48, v148
	v_lshlrev_b32_e32 v199, 2, v199
	global_load_dword v193, v199, s[30:31]
	v_add_u32_e32 v198, 0x80, v148
	v_lshlrev_b32_e32 v198, 2, v198
	global_load_dword v194, v198, s[30:31]
	v_add_u32_e32 v199, 0x90, v148
	v_lshlrev_b32_e32 v199, 2, v199
	global_load_dword v195, v199, s[30:31]
	v_add_u32_e32 v198, 0xa0, v148
	v_lshlrev_b32_e32 v198, 2, v198
	global_load_dword v196, v198, s[30:31]
	v_add_u32_e32 v199, 0xb0, v148
	v_lshlrev_b32_e32 v199, 2, v199
	global_load_dword v197, v199, s[30:31]
	v_ashrrev_i32_e32 v149, 31, v148
	v_lshl_add_u64 v[146:147], v[148:149], 2, s[30:31]
	v_lshlrev_b64 v[158:159], 12, v[148:149]
	v_lshl_or_b32 v146, s14, 8, v151
	v_ashrrev_i32_e32 v147, 31, v146
	v_or_b32_e32 v156, 16, v148
	v_lshlrev_b64 v[146:147], 1, v[146:147]
	v_lshl_add_u64 v[158:159], s[42:43], 0, v[158:159]
	v_ashrrev_i32_e32 v157, 31, v156
	v_lshl_add_u64 v[158:159], v[158:159], 0, v[146:147]
	s_waitcnt vmcnt(7)
	v_fmamk_f32 v149, v190, 0x3b000000, v155
	v_mul_f32_e32 v160, 0x4b800000, v149
	v_cmp_gt_f32_e32 vcc, s60, v149
	s_nop 1
	v_cndmask_b32_e32 v149, v149, v160, vcc
	v_rsq_f32_e32 v149, v149
	v_lshl_add_u64 v[160:161], v[156:157], 2, s[30:31]
	v_mul_f32_e32 v162, 0x45800000, v149
	v_cndmask_b32_e32 v162, v149, v162, vcc
	v_pk_mul_f32 v[126:127], v[126:127], v[162:163] op_sel_hi:[1,0]
	v_pk_mul_f32 v[124:125], v[124:125], v[162:163] op_sel_hi:[1,0]
	v_pk_mul_f32 v[122:123], v[122:123], v[162:163] op_sel_hi:[1,0]
	v_pk_mul_f32 v[120:121], v[120:121], v[162:163] op_sel_hi:[1,0]
	v_pk_mul_f32 v[118:119], v[118:119], v[162:163] op_sel_hi:[1,0]
	v_pk_mul_f32 v[116:117], v[116:117], v[162:163] op_sel_hi:[1,0]
	v_pk_mul_f32 v[164:165], v[114:115], v[162:163] op_sel_hi:[1,0]
	v_pk_mul_f32 v[162:163], v[112:113], v[162:163] op_sel_hi:[1,0]
	v_cvt_pk_bf16_f32 v112, v124, v125
	v_cvt_pk_bf16_f32 v113, v126, v127
	v_cvt_pk_bf16_f32 v114, v120, v121
	v_cvt_pk_bf16_f32 v115, v122, v123
	v_cvt_pk_bf16_f32 v116, v116, v117
	v_cvt_pk_bf16_f32 v117, v118, v119
	v_cvt_pk_bf16_f32 v118, v162, v163
	v_cvt_pk_bf16_f32 v119, v164, v165
	global_store_dwordx4 v[158:159], v[112:115], off
	global_store_dwordx4 v[158:159], v[116:119], off offset:256
	v_lshlrev_b64 v[114:115], 12, v[156:157]
	v_or_b32_e32 v112, 32, v148
	v_lshl_add_u64 v[114:115], s[42:43], 0, v[114:115]
	v_ashrrev_i32_e32 v113, 31, v112
	v_lshl_add_u64 v[114:115], v[114:115], 0, v[146:147]
	s_waitcnt vmcnt(8)
	v_fmamk_f32 v116, v191, 0x3b000000, v155
	v_mul_f32_e32 v117, 0x4b800000, v116
	v_cmp_gt_f32_e32 vcc, s60, v116
	s_nop 1
	v_cndmask_b32_e32 v116, v116, v117, vcc
	v_rsq_f32_e32 v118, v116
	v_lshl_add_u64 v[116:117], v[112:113], 2, s[30:31]
	v_mul_f32_e32 v119, 0x45800000, v118
	v_cndmask_b32_e32 v118, v118, v119, vcc
	v_pk_mul_f32 v[110:111], v[110:111], v[118:119] op_sel_hi:[1,0]
	v_pk_mul_f32 v[108:109], v[108:109], v[118:119] op_sel_hi:[1,0]
	v_pk_mul_f32 v[106:107], v[106:107], v[118:119] op_sel_hi:[1,0]
	v_pk_mul_f32 v[104:105], v[104:105], v[118:119] op_sel_hi:[1,0]
	v_pk_mul_f32 v[102:103], v[102:103], v[118:119] op_sel_hi:[1,0]
	v_pk_mul_f32 v[100:101], v[100:101], v[118:119] op_sel_hi:[1,0]
	v_pk_mul_f32 v[120:121], v[98:99], v[118:119] op_sel_hi:[1,0]
	v_pk_mul_f32 v[118:119], v[96:97], v[118:119] op_sel_hi:[1,0]
	v_cvt_pk_bf16_f32 v96, v108, v109
	v_cvt_pk_bf16_f32 v97, v110, v111
	v_cvt_pk_bf16_f32 v98, v104, v105
	v_cvt_pk_bf16_f32 v99, v106, v107
	v_cvt_pk_bf16_f32 v100, v100, v101
	v_cvt_pk_bf16_f32 v101, v102, v103
	v_cvt_pk_bf16_f32 v102, v118, v119
	v_cvt_pk_bf16_f32 v103, v120, v121
	global_store_dwordx4 v[114:115], v[96:99], off
	global_store_dwordx4 v[114:115], v[100:103], off offset:256
	v_lshlrev_b64 v[98:99], 12, v[112:113]
	v_or_b32_e32 v96, 48, v148
	v_lshl_add_u64 v[98:99], s[42:43], 0, v[98:99]
	v_ashrrev_i32_e32 v97, 31, v96
	v_lshl_add_u64 v[98:99], v[98:99], 0, v[146:147]
	s_waitcnt vmcnt(9)
	v_fmamk_f32 v100, v192, 0x3b000000, v155
	v_mul_f32_e32 v101, 0x4b800000, v100
	v_cmp_gt_f32_e32 vcc, s60, v100
	s_nop 1
	v_cndmask_b32_e32 v100, v100, v101, vcc
	v_rsq_f32_e32 v102, v100
	v_lshl_add_u64 v[100:101], v[96:97], 2, s[30:31]
	v_mul_f32_e32 v103, 0x45800000, v102
	v_cndmask_b32_e32 v102, v102, v103, vcc
	v_pk_mul_f32 v[94:95], v[94:95], v[102:103] op_sel_hi:[1,0]
	v_pk_mul_f32 v[92:93], v[92:93], v[102:103] op_sel_hi:[1,0]
	v_pk_mul_f32 v[90:91], v[90:91], v[102:103] op_sel_hi:[1,0]
	v_pk_mul_f32 v[88:89], v[88:89], v[102:103] op_sel_hi:[1,0]
	v_pk_mul_f32 v[86:87], v[86:87], v[102:103] op_sel_hi:[1,0]
	v_pk_mul_f32 v[84:85], v[84:85], v[102:103] op_sel_hi:[1,0]
	v_pk_mul_f32 v[104:105], v[82:83], v[102:103] op_sel_hi:[1,0]
	v_pk_mul_f32 v[102:103], v[80:81], v[102:103] op_sel_hi:[1,0]
	v_cvt_pk_bf16_f32 v80, v92, v93
	v_cvt_pk_bf16_f32 v81, v94, v95
	v_cvt_pk_bf16_f32 v82, v88, v89
	v_cvt_pk_bf16_f32 v83, v90, v91
	v_cvt_pk_bf16_f32 v84, v84, v85
	v_cvt_pk_bf16_f32 v85, v86, v87
	v_cvt_pk_bf16_f32 v86, v102, v103
	v_cvt_pk_bf16_f32 v87, v104, v105
	global_store_dwordx4 v[98:99], v[80:83], off
	global_store_dwordx4 v[98:99], v[84:87], off offset:256
	v_lshlrev_b64 v[82:83], 12, v[96:97]
	v_add_u32_e32 v80, 0x80, v148
	v_lshl_add_u64 v[82:83], s[42:43], 0, v[82:83]
	v_ashrrev_i32_e32 v81, 31, v80
	v_lshl_add_u64 v[82:83], v[82:83], 0, v[146:147]
	s_waitcnt vmcnt(10)
	v_fmamk_f32 v84, v193, 0x3b000000, v155
	v_mul_f32_e32 v85, 0x4b800000, v84
	v_cmp_gt_f32_e32 vcc, s60, v84
	s_nop 1
	v_cndmask_b32_e32 v84, v84, v85, vcc
	v_rsq_f32_e32 v86, v84
	v_lshl_add_u64 v[84:85], v[80:81], 2, s[30:31]
	v_mul_f32_e32 v87, 0x45800000, v86
	v_cndmask_b32_e32 v86, v86, v87, vcc
	v_pk_mul_f32 v[78:79], v[78:79], v[86:87] op_sel_hi:[1,0]
	v_pk_mul_f32 v[76:77], v[76:77], v[86:87] op_sel_hi:[1,0]
	v_pk_mul_f32 v[74:75], v[74:75], v[86:87] op_sel_hi:[1,0]
	v_pk_mul_f32 v[72:73], v[72:73], v[86:87] op_sel_hi:[1,0]
	v_pk_mul_f32 v[70:71], v[70:71], v[86:87] op_sel_hi:[1,0]
	v_pk_mul_f32 v[68:69], v[68:69], v[86:87] op_sel_hi:[1,0]
	v_pk_mul_f32 v[88:89], v[66:67], v[86:87] op_sel_hi:[1,0]
	v_pk_mul_f32 v[86:87], v[64:65], v[86:87] op_sel_hi:[1,0]
	v_cvt_pk_bf16_f32 v64, v76, v77
	v_cvt_pk_bf16_f32 v65, v78, v79
	v_cvt_pk_bf16_f32 v66, v72, v73
	v_cvt_pk_bf16_f32 v67, v74, v75
	v_cvt_pk_bf16_f32 v68, v68, v69
	v_cvt_pk_bf16_f32 v69, v70, v71
	v_cvt_pk_bf16_f32 v70, v86, v87
	v_cvt_pk_bf16_f32 v71, v88, v89
	global_store_dwordx4 v[82:83], v[64:67], off
	global_store_dwordx4 v[82:83], v[68:71], off offset:256
	v_lshlrev_b64 v[66:67], 12, v[80:81]
	v_add_u32_e32 v64, 0x90, v148
	v_lshl_add_u64 v[66:67], s[42:43], 0, v[66:67]
	v_ashrrev_i32_e32 v65, 31, v64
	v_lshl_add_u64 v[66:67], v[66:67], 0, v[146:147]
	s_waitcnt vmcnt(11)
	v_fmamk_f32 v68, v194, 0x3b000000, v155
	v_mul_f32_e32 v69, 0x4b800000, v68
	v_cmp_gt_f32_e32 vcc, s60, v68
	s_nop 1
	v_cndmask_b32_e32 v68, v68, v69, vcc
	v_rsq_f32_e32 v70, v68
	v_lshl_add_u64 v[68:69], v[64:65], 2, s[30:31]
	v_mul_f32_e32 v71, 0x45800000, v70
	v_cndmask_b32_e32 v70, v70, v71, vcc
	v_pk_mul_f32 v[62:63], v[62:63], v[70:71] op_sel_hi:[1,0]
	v_pk_mul_f32 v[60:61], v[60:61], v[70:71] op_sel_hi:[1,0]
	v_pk_mul_f32 v[58:59], v[58:59], v[70:71] op_sel_hi:[1,0]
	v_pk_mul_f32 v[56:57], v[56:57], v[70:71] op_sel_hi:[1,0]
	v_pk_mul_f32 v[54:55], v[54:55], v[70:71] op_sel_hi:[1,0]
	v_pk_mul_f32 v[52:53], v[52:53], v[70:71] op_sel_hi:[1,0]
	v_pk_mul_f32 v[72:73], v[50:51], v[70:71] op_sel_hi:[1,0]
	v_pk_mul_f32 v[70:71], v[48:49], v[70:71] op_sel_hi:[1,0]
	v_cvt_pk_bf16_f32 v48, v60, v61
	v_cvt_pk_bf16_f32 v49, v62, v63
	v_cvt_pk_bf16_f32 v50, v56, v57
	v_cvt_pk_bf16_f32 v51, v58, v59
	v_cvt_pk_bf16_f32 v52, v52, v53
	v_cvt_pk_bf16_f32 v53, v54, v55
	v_cvt_pk_bf16_f32 v54, v70, v71
	v_cvt_pk_bf16_f32 v55, v72, v73
	global_store_dwordx4 v[66:67], v[48:51], off
	global_store_dwordx4 v[66:67], v[52:55], off offset:256
	v_lshlrev_b64 v[50:51], 12, v[64:65]
	v_add_u32_e32 v48, 0xa0, v148
	v_lshl_add_u64 v[50:51], s[42:43], 0, v[50:51]
	v_ashrrev_i32_e32 v49, 31, v48
	v_lshl_add_u64 v[50:51], v[50:51], 0, v[146:147]
	s_waitcnt vmcnt(12)
	v_fmamk_f32 v52, v195, 0x3b000000, v155
	v_mul_f32_e32 v53, 0x4b800000, v52
	v_cmp_gt_f32_e32 vcc, s60, v52
	s_nop 1
	v_cndmask_b32_e32 v52, v52, v53, vcc
	v_rsq_f32_e32 v54, v52
	v_lshl_add_u64 v[52:53], v[48:49], 2, s[30:31]
	v_mul_f32_e32 v55, 0x45800000, v54
	v_cndmask_b32_e32 v54, v54, v55, vcc
	v_pk_mul_f32 v[46:47], v[46:47], v[54:55] op_sel_hi:[1,0]
	v_pk_mul_f32 v[44:45], v[44:45], v[54:55] op_sel_hi:[1,0]
	v_pk_mul_f32 v[42:43], v[42:43], v[54:55] op_sel_hi:[1,0]
	v_pk_mul_f32 v[40:41], v[40:41], v[54:55] op_sel_hi:[1,0]
	v_pk_mul_f32 v[38:39], v[38:39], v[54:55] op_sel_hi:[1,0]
	v_pk_mul_f32 v[36:37], v[36:37], v[54:55] op_sel_hi:[1,0]
	v_pk_mul_f32 v[56:57], v[34:35], v[54:55] op_sel_hi:[1,0]
	v_pk_mul_f32 v[54:55], v[32:33], v[54:55] op_sel_hi:[1,0]
	v_cvt_pk_bf16_f32 v32, v44, v45
	v_cvt_pk_bf16_f32 v33, v46, v47
	v_cvt_pk_bf16_f32 v34, v40, v41
	v_cvt_pk_bf16_f32 v35, v42, v43
	v_cvt_pk_bf16_f32 v36, v36, v37
	v_cvt_pk_bf16_f32 v37, v38, v39
	v_cvt_pk_bf16_f32 v38, v54, v55
	v_cvt_pk_bf16_f32 v39, v56, v57
	global_store_dwordx4 v[50:51], v[32:35], off
	global_store_dwordx4 v[50:51], v[36:39], off offset:256
	v_lshlrev_b64 v[34:35], 12, v[48:49]
	v_add_u32_e32 v32, 0xb0, v148
	v_lshl_add_u64 v[34:35], s[42:43], 0, v[34:35]
	v_ashrrev_i32_e32 v33, 31, v32
	v_lshl_add_u64 v[34:35], v[34:35], 0, v[146:147]
	s_waitcnt vmcnt(13)
	v_fmamk_f32 v36, v196, 0x3b000000, v155
	v_mul_f32_e32 v37, 0x4b800000, v36
	v_cmp_gt_f32_e32 vcc, s60, v36
	s_nop 1
	v_cndmask_b32_e32 v36, v36, v37, vcc
	v_rsq_f32_e32 v38, v36
	v_lshl_add_u64 v[36:37], v[32:33], 2, s[30:31]
	v_mul_f32_e32 v39, 0x45800000, v38
	v_cndmask_b32_e32 v38, v38, v39, vcc
	v_pk_mul_f32 v[30:31], v[30:31], v[38:39] op_sel_hi:[1,0]
	v_pk_mul_f32 v[28:29], v[28:29], v[38:39] op_sel_hi:[1,0]
	v_pk_mul_f32 v[26:27], v[26:27], v[38:39] op_sel_hi:[1,0]
	v_pk_mul_f32 v[24:25], v[24:25], v[38:39] op_sel_hi:[1,0]
	v_pk_mul_f32 v[22:23], v[22:23], v[38:39] op_sel_hi:[1,0]
	v_pk_mul_f32 v[20:21], v[20:21], v[38:39] op_sel_hi:[1,0]
	v_pk_mul_f32 v[40:41], v[18:19], v[38:39] op_sel_hi:[1,0]
	v_pk_mul_f32 v[38:39], v[16:17], v[38:39] op_sel_hi:[1,0]
	v_cvt_pk_bf16_f32 v16, v28, v29
	v_cvt_pk_bf16_f32 v17, v30, v31
	v_cvt_pk_bf16_f32 v18, v24, v25
	v_cvt_pk_bf16_f32 v19, v26, v27
	v_cvt_pk_bf16_f32 v20, v20, v21
	v_cvt_pk_bf16_f32 v21, v22, v23
	v_cvt_pk_bf16_f32 v22, v38, v39
	v_cvt_pk_bf16_f32 v23, v40, v41
	global_store_dwordx4 v[34:35], v[16:19], off
	global_store_dwordx4 v[34:35], v[20:23], off offset:256
	s_andn2_b64 vcc, exec, s[6:7]
	s_waitcnt vmcnt(14)
	v_fmamk_f32 v16, v197, 0x3b000000, v155
	v_mul_f32_e32 v17, 0x4b800000, v16
	v_cmp_gt_f32_e64 s[6:7], s60, v16
	s_nop 1
	v_cndmask_b32_e64 v16, v16, v17, s[6:7]
	v_rsq_f32_e32 v18, v16
	v_lshlrev_b64 v[16:17], 12, v[32:33]
	v_lshl_add_u64 v[16:17], s[42:43], 0, v[16:17]
	v_lshl_add_u64 v[16:17], v[16:17], 0, v[146:147]
	v_mul_f32_e32 v19, 0x45800000, v18
	v_cndmask_b32_e64 v18, v18, v19, s[6:7]
	v_pk_mul_f32 v[14:15], v[14:15], v[18:19] op_sel_hi:[1,0]
	v_pk_mul_f32 v[12:13], v[12:13], v[18:19] op_sel_hi:[1,0]
	v_pk_mul_f32 v[10:11], v[10:11], v[18:19] op_sel_hi:[1,0]
	v_pk_mul_f32 v[8:9], v[8:9], v[18:19] op_sel_hi:[1,0]
	v_pk_mul_f32 v[6:7], v[6:7], v[18:19] op_sel_hi:[1,0]
	v_pk_mul_f32 v[4:5], v[4:5], v[18:19] op_sel_hi:[1,0]
	v_pk_mul_f32 v[20:21], v[2:3], v[18:19] op_sel_hi:[1,0]
	v_pk_mul_f32 v[18:19], v[0:1], v[18:19] op_sel_hi:[1,0]
	v_cvt_pk_bf16_f32 v0, v12, v13
	v_cvt_pk_bf16_f32 v1, v14, v15
	v_cvt_pk_bf16_f32 v2, v8, v9
	v_cvt_pk_bf16_f32 v3, v10, v11
	s_mov_b64 s[6:7], -1
	v_cvt_pk_bf16_f32 v4, v4, v5
	v_cvt_pk_bf16_f32 v5, v6, v7
	v_cvt_pk_bf16_f32 v6, v18, v19
	v_cvt_pk_bf16_f32 v7, v20, v21
	global_store_dwordx4 v[16:17], v[0:3], off
	global_store_dwordx4 v[16:17], v[4:7], off offset:256
	s_cbranch_vccnz .LBB0_874
	s_andn2_b64 vcc, exec, s[10:11]
	s_cbranch_vccnz .LBB0_873
	s_barrier
	s_branch .LBB0_873

.LBB0_1179:
	s_mulk_i32 s85, 0x3e00
	v_lshrrev_b32_e32 v83, 4, v219
	s_add_i32 s88, s88, s85
	v_mul_u32_u24_e32 v64, 0x210, v227
	v_and_b32_e32 v82, 15, v220
	v_or_b32_e32 v68, s86, v83
	v_add3_u32 v81, s88, v64, v214
	v_lshlrev_b32_e32 v214, 4, v82
	v_ashrrev_i32_e32 v69, 31, v68
	v_lshl_add_u64 v[64:65], s[10:11], 0, v[214:215]
	v_lshl_add_u64 v[66:67], s[12:13], 0, v[214:215]
	v_lshlrev_b64 v[70:71], 12, v[68:69]
	v_lshlrev_b64 v[74:75], 13, v[68:69]
	v_lshl_add_u64 v[78:79], v[64:65], 0, v[70:71]
	v_lshl_add_u64 v[74:75], v[66:67], 0, v[74:75]
	s_waitcnt lgkmcnt(0)
	s_barrier
	global_load_dwordx4 v[70:73], v[78:79], off
	v_mov_b32_e32 v69, v235
	global_load_dwordx4 v[74:77], v[74:75], off nt
	v_mov_b32_e32 v195, 0
	v_or_b32_e32 v192, 4, v68
	v_lshlrev_b32_e32 v194, 12, v192
	v_lshl_add_u64 v[196:197], v[64:65], 0, v[194:195]
	global_load_dwordx4 v[136:139], v[196:197], off
	v_lshlrev_b32_e32 v194, 13, v192
	v_lshl_add_u64 v[198:199], v[66:67], 0, v[194:195]
	global_load_dwordx4 v[140:143], v[198:199], off nt
	v_or_b32_e32 v192, 8, v68
	v_lshlrev_b32_e32 v194, 12, v192
	v_lshl_add_u64 v[196:197], v[64:65], 0, v[194:195]
	global_load_dwordx4 v[144:147], v[196:197], off
	v_lshlrev_b32_e32 v194, 13, v192
	v_lshl_add_u64 v[198:199], v[66:67], 0, v[194:195]
	global_load_dwordx4 v[148:151], v[198:199], off nt
	v_or_b32_e32 v192, 12, v68
	v_lshlrev_b32_e32 v194, 12, v192
	v_lshl_add_u64 v[196:197], v[64:65], 0, v[194:195]
	global_load_dwordx4 v[152:155], v[196:197], off
	v_lshlrev_b32_e32 v194, 13, v192
	v_lshl_add_u64 v[198:199], v[66:67], 0, v[194:195]
	global_load_dwordx4 v[156:159], v[198:199], off nt
	v_or_b32_e32 v192, 16, v68
	v_lshlrev_b32_e32 v194, 12, v192
	v_lshl_add_u64 v[196:197], v[64:65], 0, v[194:195]
	global_load_dwordx4 v[160:163], v[196:197], off
	v_lshlrev_b32_e32 v194, 13, v192
	v_lshl_add_u64 v[198:199], v[66:67], 0, v[194:195]
	global_load_dwordx4 v[164:167], v[198:199], off nt
	v_or_b32_e32 v192, 20, v68
	v_lshlrev_b32_e32 v194, 12, v192
	v_lshl_add_u64 v[196:197], v[64:65], 0, v[194:195]
	global_load_dwordx4 v[168:171], v[196:197], off
	v_lshlrev_b32_e32 v194, 13, v192
	v_lshl_add_u64 v[198:199], v[66:67], 0, v[194:195]
	global_load_dwordx4 v[172:175], v[198:199], off nt
	v_or_b32_e32 v192, 24, v68
	v_lshlrev_b32_e32 v194, 12, v192
	v_lshl_add_u64 v[196:197], v[64:65], 0, v[194:195]
	global_load_dwordx4 v[176:179], v[196:197], off
	v_lshlrev_b32_e32 v194, 13, v192
	v_lshl_add_u64 v[198:199], v[66:67], 0, v[194:195]
	global_load_dwordx4 v[180:183], v[198:199], off nt
	v_or_b32_e32 v192, 28, v68
	v_lshlrev_b32_e32 v194, 12, v192
	v_lshl_add_u64 v[196:197], v[64:65], 0, v[194:195]
	global_load_dwordx4 v[184:187], v[196:197], off
	v_lshlrev_b32_e32 v194, 13, v192
	v_lshl_add_u64 v[198:199], v[66:67], 0, v[194:195]
	global_load_dwordx4 v[188:191], v[198:199], off nt
	s_nop 0
	v_permlane32_swap_b32_e32 v235, v69
	v_add_f32_e32 v69, v235, v69
	v_div_scale_f32 v80, s[6:7], v69, v69, 1.0
	v_rcp_f32_e32 v84, v80
	s_mov_b64 s[44:45], 0
	v_fma_f32 v85, -v80, v84, 1.0
	v_fmac_f32_e32 v84, v85, v84
	v_div_scale_f32 v85, vcc, 1.0, v69, 1.0
	v_mul_f32_e32 v86, v85, v84
	v_fma_f32 v87, -v80, v86, v85
	v_fmac_f32_e32 v86, v87, v84
	v_fma_f32 v80, -v80, v86, v85
	v_div_fmas_f32 v80, v80, v84, v86
	v_div_fixup_f32 v80, v80, v69, 1.0
	v_pk_mul_f32 v[0:1], v[0:1], v[80:81] op_sel_hi:[1,0]
	v_pk_mul_f32 v[2:3], v[2:3], v[80:81] op_sel_hi:[1,0]
	v_pk_mul_f32 v[48:49], v[48:49], v[80:81] op_sel_hi:[1,0]
	v_pk_mul_f32 v[50:51], v[50:51], v[80:81] op_sel_hi:[1,0]
	v_pk_mul_f32 v[32:33], v[32:33], v[80:81] op_sel_hi:[1,0]
	v_pk_mul_f32 v[34:35], v[34:35], v[80:81] op_sel_hi:[1,0]
	v_pk_mul_f32 v[16:17], v[16:17], v[80:81] op_sel_hi:[1,0]
	v_pk_mul_f32 v[18:19], v[18:19], v[80:81] op_sel_hi:[1,0]
	ds_write_b128 v81, v[0:3] offset:384
	v_pk_mul_f32 v[0:1], v[4:5], v[80:81] op_sel_hi:[1,0]
	v_pk_mul_f32 v[2:3], v[6:7], v[80:81] op_sel_hi:[1,0]
	ds_write_b128 v81, v[48:51]
	v_pk_mul_f32 v[48:49], v[52:53], v[80:81] op_sel_hi:[1,0]
	v_pk_mul_f32 v[50:51], v[54:55], v[80:81] op_sel_hi:[1,0]
	ds_write_b128 v81, v[32:35] offset:128
	v_pk_mul_f32 v[32:33], v[36:37], v[80:81] op_sel_hi:[1,0]
	v_pk_mul_f32 v[34:35], v[38:39], v[80:81] op_sel_hi:[1,0]
	ds_write_b128 v81, v[16:19] offset:256
	v_pk_mul_f32 v[16:17], v[20:21], v[80:81] op_sel_hi:[1,0]
	v_pk_mul_f32 v[18:19], v[22:23], v[80:81] op_sel_hi:[1,0]
	ds_write_b128 v81, v[0:3] offset:416
	v_pk_mul_f32 v[0:1], v[8:9], v[80:81] op_sel_hi:[1,0]
	v_pk_mul_f32 v[2:3], v[10:11], v[80:81] op_sel_hi:[1,0]
	ds_write_b128 v81, v[48:51] offset:32
	v_pk_mul_f32 v[48:49], v[56:57], v[80:81] op_sel_hi:[1,0]
	v_pk_mul_f32 v[50:51], v[58:59], v[80:81] op_sel_hi:[1,0]
	ds_write_b128 v81, v[32:35] offset:160
	v_pk_mul_f32 v[32:33], v[40:41], v[80:81] op_sel_hi:[1,0]
	v_pk_mul_f32 v[34:35], v[42:43], v[80:81] op_sel_hi:[1,0]
	ds_write_b128 v81, v[16:19] offset:288
	v_pk_mul_f32 v[16:17], v[24:25], v[80:81] op_sel_hi:[1,0]
	v_pk_mul_f32 v[18:19], v[26:27], v[80:81] op_sel_hi:[1,0]
	ds_write_b128 v81, v[0:3] offset:448
	v_pk_mul_f32 v[0:1], v[12:13], v[80:81] op_sel_hi:[1,0]
	v_pk_mul_f32 v[2:3], v[14:15], v[80:81] op_sel_hi:[1,0]
	ds_write_b128 v81, v[48:51] offset:64
	v_pk_mul_f32 v[48:49], v[60:61], v[80:81] op_sel_hi:[1,0]
	v_pk_mul_f32 v[50:51], v[62:63], v[80:81] op_sel_hi:[1,0]
	ds_write_b128 v81, v[32:35] offset:192
	v_pk_mul_f32 v[32:33], v[44:45], v[80:81] op_sel_hi:[1,0]
	v_pk_mul_f32 v[34:35], v[46:47], v[80:81] op_sel_hi:[1,0]
	ds_write_b128 v81, v[16:19] offset:320
	v_pk_mul_f32 v[16:17], v[28:29], v[80:81] op_sel_hi:[1,0]
	v_pk_mul_f32 v[18:19], v[30:31], v[80:81] op_sel_hi:[1,0]
	ds_write_b128 v81, v[0:3] offset:480
	v_lshlrev_b32_e32 v0, 5, v82
	v_mul_u32_u24_e32 v1, 0x210, v83
	ds_write_b128 v81, v[48:51] offset:96
	ds_write_b128 v81, v[32:35] offset:224
	ds_write_b128 v81, v[16:19] offset:352
	v_add3_u32 v0, s88, v0, v1
	ds_read_b128 v[2:5], v0
	ds_read_b128 v[6:9], v0 offset:16
	v_or_b32_e32 v18, 4, v68
	v_ashrrev_i32_e32 v19, 31, v18
	s_and_b64 vcc, exec, s[16:17]
	s_waitcnt vmcnt(15)
	v_lshlrev_b32_e32 v10, 16, v70
	v_and_b32_e32 v11, 0xffff0000, v70
	s_waitcnt vmcnt(14)
	v_lshlrev_b32_e32 v12, 16, v74
	v_and_b32_e32 v13, 0xffff0000, v74
	s_waitcnt lgkmcnt(1)
	v_pk_fma_f32 v[10:11], v[2:3], v[12:13], v[10:11]
	v_lshlrev_b32_e32 v2, 16, v71
	v_and_b32_e32 v3, 0xffff0000, v71
	v_lshlrev_b32_e32 v12, 16, v75
	v_and_b32_e32 v13, 0xffff0000, v75
	v_pk_fma_f32 v[12:13], v[4:5], v[12:13], v[2:3]
	v_lshlrev_b32_e32 v2, 16, v72
	v_and_b32_e32 v3, 0xffff0000, v72
	v_lshlrev_b32_e32 v4, 16, v76
	v_and_b32_e32 v5, 0xffff0000, v76
	s_waitcnt lgkmcnt(0)
	v_pk_fma_f32 v[14:15], v[6:7], v[4:5], v[2:3]
	v_lshlrev_b32_e32 v2, 16, v73
	v_and_b32_e32 v3, 0xffff0000, v73
	v_lshlrev_b32_e32 v4, 16, v77
	v_and_b32_e32 v5, 0xffff0000, v77
	v_pk_fma_f32 v[16:17], v[8:9], v[4:5], v[2:3]
	v_cvt_pk_bf16_f32 v6, v10, v11
	v_cvt_pk_bf16_f32 v7, v12, v13
	v_cvt_pk_bf16_f32 v8, v14, v15
	v_cvt_pk_bf16_f32 v9, v16, v17
	v_lshlrev_b64 v[2:3], 12, v[18:19]
	global_store_dwordx4 v[78:79], v[6:9], off
	v_lshl_add_u64 v[22:23], v[64:65], 0, v[2:3]
	s_nop 1
	s_waitcnt vmcnt(14)
	v_mov_b64_e32 v[2:3], v[136:137]
	v_mov_b64_e32 v[4:5], v[138:139]
	v_lshlrev_b64 v[6:7], 13, v[18:19]
	v_lshl_add_u64 v[6:7], v[66:67], 0, v[6:7]
	s_nop 1
	s_waitcnt vmcnt(13)
	v_mov_b64_e32 v[6:7], v[140:141]
	v_mov_b64_e32 v[8:9], v[142:143]
	v_or_b32_e32 v10, 8, v68
	v_ashrrev_i32_e32 v11, 31, v10
	v_lshlrev_b64 v[12:13], 12, v[10:11]
	v_lshlrev_b64 v[10:11], 13, v[10:11]
	v_lshl_add_u64 v[24:25], v[64:65], 0, v[12:13]
	v_lshl_add_u64 v[26:27], v[66:67], 0, v[10:11]
	s_nop 1
	s_waitcnt vmcnt(12)
	v_mov_b64_e32 v[10:11], v[144:145]
	v_mov_b64_e32 v[12:13], v[146:147]
	ds_read_b128 v[14:17], v0 offset:2112
	ds_read_b128 v[18:21], v0 offset:2128
	v_lshlrev_b32_e32 v28, 16, v2
	v_and_b32_e32 v29, 0xffff0000, v2
	v_lshlrev_b32_e32 v2, 16, v3
	v_and_b32_e32 v3, 0xffff0000, v3
	v_lshlrev_b32_e32 v30, 16, v4
	v_and_b32_e32 v31, 0xffff0000, v4
	v_lshlrev_b32_e32 v4, 16, v5
	v_and_b32_e32 v5, 0xffff0000, v5
	v_lshlrev_b32_e32 v32, 16, v6
	v_and_b32_e32 v33, 0xffff0000, v6
	v_lshlrev_b32_e32 v6, 16, v7
	v_and_b32_e32 v7, 0xffff0000, v7
	v_lshlrev_b32_e32 v34, 16, v8
	v_and_b32_e32 v35, 0xffff0000, v8
	v_lshlrev_b32_e32 v8, 16, v9
	v_and_b32_e32 v9, 0xffff0000, v9
	s_waitcnt lgkmcnt(1)
	v_pk_fma_f32 v[14:15], v[14:15], v[32:33], v[28:29]
	v_pk_fma_f32 v[6:7], v[16:17], v[6:7], v[2:3]
	s_waitcnt lgkmcnt(0)
	v_pk_fma_f32 v[16:17], v[18:19], v[34:35], v[30:31]
	v_pk_fma_f32 v[8:9], v[20:21], v[8:9], v[4:5]
	v_cvt_pk_bf16_f32 v2, v14, v15
	v_cvt_pk_bf16_f32 v3, v6, v7
	v_cvt_pk_bf16_f32 v4, v16, v17
	v_cvt_pk_bf16_f32 v5, v8, v9
	global_store_dwordx4 v[22:23], v[2:5], off
	s_nop 1
	s_waitcnt vmcnt(12)
	v_mov_b64_e32 v[2:3], v[148:149]
	v_mov_b64_e32 v[4:5], v[150:151]
	v_or_b32_e32 v6, 12, v68
	v_ashrrev_i32_e32 v7, 31, v6
	v_lshlrev_b64 v[8:9], 12, v[6:7]
	v_lshlrev_b64 v[6:7], 13, v[6:7]
	v_lshl_add_u64 v[22:23], v[64:65], 0, v[8:9]
	v_lshl_add_u64 v[26:27], v[66:67], 0, v[6:7]
	s_nop 1
	s_waitcnt vmcnt(11)
	v_mov_b64_e32 v[6:7], v[152:153]
	v_mov_b64_e32 v[8:9], v[154:155]
	ds_read_b128 v[14:17], v0 offset:4224
	ds_read_b128 v[18:21], v0 offset:4240
	v_lshlrev_b32_e32 v28, 16, v10
	v_and_b32_e32 v29, 0xffff0000, v10
	v_lshlrev_b32_e32 v10, 16, v11
	v_and_b32_e32 v11, 0xffff0000, v11
	v_lshlrev_b32_e32 v30, 16, v12
	v_and_b32_e32 v31, 0xffff0000, v12
	v_lshlrev_b32_e32 v12, 16, v13
	v_and_b32_e32 v13, 0xffff0000, v13
	v_lshlrev_b32_e32 v32, 16, v2
	v_and_b32_e32 v33, 0xffff0000, v2
	v_lshlrev_b32_e32 v2, 16, v3
	v_and_b32_e32 v3, 0xffff0000, v3
	v_lshlrev_b32_e32 v34, 16, v4
	v_and_b32_e32 v35, 0xffff0000, v4
	v_lshlrev_b32_e32 v4, 16, v5
	v_and_b32_e32 v5, 0xffff0000, v5
	s_waitcnt lgkmcnt(1)
	v_pk_fma_f32 v[14:15], v[14:15], v[32:33], v[28:29]
	v_pk_fma_f32 v[10:11], v[16:17], v[2:3], v[10:11]
	s_waitcnt lgkmcnt(0)
	v_pk_fma_f32 v[16:17], v[18:19], v[34:35], v[30:31]
	v_pk_fma_f32 v[12:13], v[20:21], v[4:5], v[12:13]
	v_cvt_pk_bf16_f32 v2, v14, v15
	v_cvt_pk_bf16_f32 v3, v10, v11
	v_cvt_pk_bf16_f32 v4, v16, v17
	v_cvt_pk_bf16_f32 v5, v12, v13
	global_store_dwordx4 v[24:25], v[2:5], off
	s_nop 1
	s_waitcnt vmcnt(11)
	v_mov_b64_e32 v[2:3], v[156:157]
	v_mov_b64_e32 v[4:5], v[158:159]
	v_or_b32_e32 v10, 16, v68
	v_ashrrev_i32_e32 v11, 31, v10
	v_lshlrev_b64 v[12:13], 12, v[10:11]
	v_lshlrev_b64 v[10:11], 13, v[10:11]
	v_lshl_add_u64 v[24:25], v[64:65], 0, v[12:13]
	v_lshl_add_u64 v[26:27], v[66:67], 0, v[10:11]
	s_nop 1
	s_waitcnt vmcnt(10)
	v_mov_b64_e32 v[10:11], v[160:161]
	v_mov_b64_e32 v[12:13], v[162:163]
	ds_read_b128 v[14:17], v0 offset:6336
	ds_read_b128 v[18:21], v0 offset:6352
	v_lshlrev_b32_e32 v28, 16, v6
	v_and_b32_e32 v29, 0xffff0000, v6
	v_lshlrev_b32_e32 v6, 16, v7
	v_and_b32_e32 v7, 0xffff0000, v7
	v_lshlrev_b32_e32 v30, 16, v8
	v_and_b32_e32 v31, 0xffff0000, v8
	v_lshlrev_b32_e32 v8, 16, v9
	v_and_b32_e32 v9, 0xffff0000, v9
	v_lshlrev_b32_e32 v32, 16, v2
	v_and_b32_e32 v33, 0xffff0000, v2
	v_lshlrev_b32_e32 v2, 16, v3
	v_and_b32_e32 v3, 0xffff0000, v3
	v_lshlrev_b32_e32 v34, 16, v4
	v_and_b32_e32 v35, 0xffff0000, v4
	v_lshlrev_b32_e32 v4, 16, v5
	v_and_b32_e32 v5, 0xffff0000, v5
	s_waitcnt lgkmcnt(1)
	v_pk_fma_f32 v[14:15], v[14:15], v[32:33], v[28:29]
	v_pk_fma_f32 v[6:7], v[16:17], v[2:3], v[6:7]
	s_waitcnt lgkmcnt(0)
	v_pk_fma_f32 v[16:17], v[18:19], v[34:35], v[30:31]
	v_pk_fma_f32 v[8:9], v[20:21], v[4:5], v[8:9]
	v_cvt_pk_bf16_f32 v2, v14, v15
	v_cvt_pk_bf16_f32 v3, v6, v7
	v_cvt_pk_bf16_f32 v4, v16, v17
	v_cvt_pk_bf16_f32 v5, v8, v9
	global_store_dwordx4 v[22:23], v[2:5], off
	s_nop 1
	s_waitcnt vmcnt(10)
	v_mov_b64_e32 v[2:3], v[164:165]
	v_mov_b64_e32 v[4:5], v[166:167]
	v_or_b32_e32 v6, 20, v68
	v_ashrrev_i32_e32 v7, 31, v6
	v_lshlrev_b64 v[8:9], 12, v[6:7]
	v_lshlrev_b64 v[6:7], 13, v[6:7]
	v_lshl_add_u64 v[22:23], v[64:65], 0, v[8:9]
	v_lshl_add_u64 v[26:27], v[66:67], 0, v[6:7]
	s_nop 1
	s_waitcnt vmcnt(9)
	v_mov_b64_e32 v[6:7], v[168:169]
	v_mov_b64_e32 v[8:9], v[170:171]
	ds_read_b128 v[14:17], v0 offset:8448
	ds_read_b128 v[18:21], v0 offset:8464
	v_lshlrev_b32_e32 v28, 16, v10
	v_and_b32_e32 v29, 0xffff0000, v10
	v_lshlrev_b32_e32 v10, 16, v11
	v_and_b32_e32 v11, 0xffff0000, v11
	v_lshlrev_b32_e32 v30, 16, v12
	v_and_b32_e32 v31, 0xffff0000, v12
	v_lshlrev_b32_e32 v12, 16, v13
	v_and_b32_e32 v13, 0xffff0000, v13
	v_lshlrev_b32_e32 v32, 16, v2
	v_and_b32_e32 v33, 0xffff0000, v2
	v_lshlrev_b32_e32 v2, 16, v3
	v_and_b32_e32 v3, 0xffff0000, v3
	v_lshlrev_b32_e32 v34, 16, v4
	v_and_b32_e32 v35, 0xffff0000, v4
	v_lshlrev_b32_e32 v4, 16, v5
	v_and_b32_e32 v5, 0xffff0000, v5
	s_waitcnt lgkmcnt(1)
	v_pk_fma_f32 v[14:15], v[14:15], v[32:33], v[28:29]
	v_pk_fma_f32 v[10:11], v[16:17], v[2:3], v[10:11]
	s_waitcnt lgkmcnt(0)
	v_pk_fma_f32 v[16:17], v[18:19], v[34:35], v[30:31]
	v_pk_fma_f32 v[12:13], v[20:21], v[4:5], v[12:13]
	v_cvt_pk_bf16_f32 v2, v14, v15
	v_cvt_pk_bf16_f32 v3, v10, v11
	v_cvt_pk_bf16_f32 v4, v16, v17
	v_cvt_pk_bf16_f32 v5, v12, v13
	global_store_dwordx4 v[24:25], v[2:5], off
	s_nop 1
	s_waitcnt vmcnt(9)
	v_mov_b64_e32 v[2:3], v[172:173]
	v_mov_b64_e32 v[4:5], v[174:175]
	v_or_b32_e32 v10, 24, v68
	v_ashrrev_i32_e32 v11, 31, v10
	v_lshlrev_b64 v[12:13], 12, v[10:11]
	v_lshlrev_b64 v[10:11], 13, v[10:11]
	v_lshl_add_u64 v[24:25], v[64:65], 0, v[12:13]
	v_lshl_add_u64 v[26:27], v[66:67], 0, v[10:11]
	s_nop 1
	s_waitcnt vmcnt(8)
	v_mov_b64_e32 v[10:11], v[176:177]
	v_mov_b64_e32 v[12:13], v[178:179]
	ds_read_b128 v[14:17], v0 offset:10560
	ds_read_b128 v[18:21], v0 offset:10576
	v_lshlrev_b32_e32 v28, 16, v6
	v_and_b32_e32 v29, 0xffff0000, v6
	v_lshlrev_b32_e32 v6, 16, v7
	v_and_b32_e32 v7, 0xffff0000, v7
	v_lshlrev_b32_e32 v30, 16, v8
	v_and_b32_e32 v31, 0xffff0000, v8
	v_lshlrev_b32_e32 v8, 16, v9
	v_and_b32_e32 v9, 0xffff0000, v9
	v_lshlrev_b32_e32 v32, 16, v2
	v_and_b32_e32 v33, 0xffff0000, v2
	v_lshlrev_b32_e32 v2, 16, v3
	v_and_b32_e32 v3, 0xffff0000, v3
	v_lshlrev_b32_e32 v34, 16, v4
	v_and_b32_e32 v35, 0xffff0000, v4
	v_lshlrev_b32_e32 v4, 16, v5
	v_and_b32_e32 v5, 0xffff0000, v5
	s_waitcnt lgkmcnt(1)
	v_pk_fma_f32 v[14:15], v[14:15], v[32:33], v[28:29]
	v_pk_fma_f32 v[6:7], v[16:17], v[2:3], v[6:7]
	s_waitcnt lgkmcnt(0)
	v_pk_fma_f32 v[16:17], v[18:19], v[34:35], v[30:31]
	v_pk_fma_f32 v[8:9], v[20:21], v[4:5], v[8:9]
	v_cvt_pk_bf16_f32 v2, v14, v15
	v_cvt_pk_bf16_f32 v3, v6, v7
	v_cvt_pk_bf16_f32 v4, v16, v17
	v_cvt_pk_bf16_f32 v5, v8, v9
	global_store_dwordx4 v[22:23], v[2:5], off
	s_nop 1
	s_waitcnt vmcnt(8)
	v_mov_b64_e32 v[2:3], v[180:181]
	v_mov_b64_e32 v[4:5], v[182:183]
	v_or_b32_e32 v6, 28, v68
	v_ashrrev_i32_e32 v7, 31, v6
	v_lshlrev_b64 v[8:9], 12, v[6:7]
	v_lshlrev_b64 v[6:7], 13, v[6:7]
	v_lshl_add_u64 v[22:23], v[64:65], 0, v[8:9]
	v_lshl_add_u64 v[26:27], v[66:67], 0, v[6:7]
	s_nop 1
	s_waitcnt vmcnt(7)
	v_mov_b64_e32 v[6:7], v[184:185]
	v_mov_b64_e32 v[8:9], v[186:187]
	ds_read_b128 v[14:17], v0 offset:12672
	ds_read_b128 v[18:21], v0 offset:12688
	v_lshlrev_b32_e32 v28, 16, v10
	v_and_b32_e32 v29, 0xffff0000, v10
	v_lshlrev_b32_e32 v10, 16, v11
	v_and_b32_e32 v11, 0xffff0000, v11
	v_lshlrev_b32_e32 v30, 16, v12
	v_and_b32_e32 v31, 0xffff0000, v12
	v_lshlrev_b32_e32 v12, 16, v13
	v_and_b32_e32 v13, 0xffff0000, v13
	v_lshlrev_b32_e32 v32, 16, v2
	v_and_b32_e32 v33, 0xffff0000, v2
	v_lshlrev_b32_e32 v2, 16, v3
	v_and_b32_e32 v3, 0xffff0000, v3
	v_lshlrev_b32_e32 v34, 16, v4
	v_and_b32_e32 v35, 0xffff0000, v4
	v_lshlrev_b32_e32 v4, 16, v5
	v_and_b32_e32 v5, 0xffff0000, v5
	s_waitcnt lgkmcnt(1)
	v_pk_fma_f32 v[14:15], v[14:15], v[32:33], v[28:29]
	v_pk_fma_f32 v[10:11], v[16:17], v[2:3], v[10:11]
	s_waitcnt lgkmcnt(0)
	v_pk_fma_f32 v[16:17], v[18:19], v[34:35], v[30:31]
	v_pk_fma_f32 v[12:13], v[20:21], v[4:5], v[12:13]
	v_cvt_pk_bf16_f32 v2, v14, v15
	v_cvt_pk_bf16_f32 v3, v10, v11
	v_cvt_pk_bf16_f32 v4, v16, v17
	v_cvt_pk_bf16_f32 v5, v12, v13
	global_store_dwordx4 v[24:25], v[2:5], off
	s_nop 1
	s_waitcnt vmcnt(7)
	v_mov_b64_e32 v[2:3], v[188:189]
	v_mov_b64_e32 v[4:5], v[190:191]
	ds_read_b128 v[10:13], v0 offset:14784
	ds_read_b128 v[14:17], v0 offset:14800
	v_lshlrev_b32_e32 v0, 16, v6
	v_and_b32_e32 v1, 0xffff0000, v6
	v_lshlrev_b32_e32 v6, 16, v7
	v_and_b32_e32 v7, 0xffff0000, v7
	v_lshlrev_b32_e32 v18, 16, v8
	v_and_b32_e32 v19, 0xffff0000, v8
	v_lshlrev_b32_e32 v8, 16, v9
	v_and_b32_e32 v9, 0xffff0000, v9
	v_lshlrev_b32_e32 v20, 16, v2
	v_and_b32_e32 v21, 0xffff0000, v2
	v_lshlrev_b32_e32 v2, 16, v3
	v_and_b32_e32 v3, 0xffff0000, v3
	v_lshlrev_b32_e32 v24, 16, v4
	v_and_b32_e32 v25, 0xffff0000, v4
	v_lshlrev_b32_e32 v4, 16, v5
	v_and_b32_e32 v5, 0xffff0000, v5
	s_waitcnt lgkmcnt(1)
	v_pk_fma_f32 v[0:1], v[10:11], v[20:21], v[0:1]
	v_pk_fma_f32 v[2:3], v[12:13], v[2:3], v[6:7]
	s_waitcnt lgkmcnt(0)
	v_pk_fma_f32 v[6:7], v[14:15], v[24:25], v[18:19]
	v_pk_fma_f32 v[4:5], v[16:17], v[4:5], v[8:9]
	v_cvt_pk_bf16_f32 v0, v0, v1
	v_cvt_pk_bf16_f32 v1, v2, v3
	v_cvt_pk_bf16_f32 v2, v6, v7
	v_cvt_pk_bf16_f32 v3, v4, v5
	global_store_dwordx4 v[22:23], v[0:3], off
	s_barrier
	s_cbranch_vccnz .LBB0_1177
